# ffn_in epilogue: the column-constant loads are issued before the K-loop's closing barrier
# baseline (speedup 1.0000x reference)
; #define PG8_STAGE(bufoff, gbase, voff) do { _Pragma("unroll") for (int _i = 0; _i < 2; ++_i) \
;         __builtin_amdgcn_global_load_lds((const unsigned*)((const char*)(gbase) + (voff)[_i]), (PG8_LAS unsigned*)(lds + (bufoff) + ldsw + _i * 8192), 16, 0, 0); } while (0)
; #define PG8_LDA(dst, b, h) do { _Pragma("unroll") for (int m = 0; m < 4; ++m) _Pragma("unroll") for (int k = 0; k < 2; ++k) dst[m][k] = *(const PG8_LAS bf16x8*)(lds + PG8_SA(b, h) + aoff + m * 2048 + k * 1024); } while (0)
; #define PG8_LDB(dst, b, h) do { _Pragma("unroll") for (int n = 0; n < 2; ++n) _Pragma("unroll") for (int k = 0; k < 2; ++k) dst[n][k] = *(const PG8_LAS bf16x8*)(lds + PG8_SB(b, h) + boff + n * 2048 + k * 1024); } while (0)
; #define PG8_MMA(ai, bj, At, Bt) do { __builtin_amdgcn_s_setprio(1); _Pragma("unroll") for (int m = 0; m < 4; ++m) _Pragma("unroll") for (int n = 0; n < 2; ++n) _Pragma("unroll") for (int k = 0; k < 2; ++k) \
;         acc[ai][bj][m][n] = __builtin_amdgcn_mfma_f32_16x16x32_bf16(Bt[n][k], At[m][k], acc[ai][bj][m][n], 0, 0, 0); __builtin_amdgcn_s_setprio(0); } while (0)
; #define PG8_WAIT_V(n) asm volatile("s_waitcnt vmcnt(" #n ")" ::: "memory")
; #define PG8_WAIT_L(n) asm volatile("s_waitcnt lgkmcnt(" #n ")" ::: "memory")
; #define PG8_BAR __builtin_amdgcn_s_barrier()
; #define PG8_SCHED __builtin_amdgcn_sched_barrier(0)
; template <class Epi, class Sched, bool ALIGN_EPI = false, bool SP2 = false>
; __device__ __forceinline__ void gemm_phase(PG8_LAS unsigned char* lds, const Gemm g, const Sched& S, const Epi& E, int tid_in) {
;     ...
;             PG8_LDB(B0, 0, 0); PG8_LDB(B1, 0, 1); PG8_SCHED; PG8_LDA(At, 0, 0); PG8_STAGE(PG8_SA(1, 1), a1 + hstep, voffA);
;             PG8_WAIT_V(8); PG8_WAIT_L(0); PG8_BAR; PG8_MMA(0, 0, At, B0); PG8_MMA(0, 1, At, B1); PG8_BAR; PG8_SCHED;
;             PG8_LDA(At, 0, 1); PG8_STAGE(PG8_SB(0, 0), b2, voffB); PG8_STAGE(PG8_SB(0, 1), b2 + hstep, voffB); PG8_STAGE(PG8_SA(0, 0), a2, voffA);
;             PG8_WAIT_V(8); PG8_WAIT_L(0); PG8_BAR; PG8_MMA(1, 0, At, B0); PG8_MMA(1, 1, At, B1); PG8_BAR; PG8_SCHED;
.LBB0_1601:
	s_add_u32 s54, s52, 0xfffc0080
	s_addc_u32 s55, s53, -1
	s_add_i32 s72, 0, 0x10000
	s_cmp_eq_u32 s71, 12
	s_cselect_b32 s57, s0, s55
	s_cselect_b32 s56, s1, s54
	s_cselect_b32 s55, s43, s70
	s_cselect_b32 s54, s47, s69
	s_add_i32 s74, 0, 0x14000
	v_add_u32_e32 v76, s72, v182
	v_add_u32_e32 v94, s74, v182
	ds_read_b128 v[60:63], v76
	ds_read_b128 v[64:67], v76 offset:1024
	ds_read_b128 v[72:75], v76 offset:2048
	ds_read_b128 v[76:79], v76 offset:3072
	ds_read_b128 v[82:85], v94
	ds_read_b128 v[86:89], v94 offset:1024
	ds_read_b128 v[90:93], v94 offset:2048
	ds_read_b128 v[94:97], v94 offset:3072
	v_lshl_add_u64 v[208:209], s[52:53], 0, v[172:173]
	s_add_i32 m0, s18, 0xc000
	ds_read_b128 v[162:165], v183
	ds_read_b128 v[176:179], v183 offset:1024
	ds_read_b128 v[184:187], v183 offset:2048
	ds_read_b128 v[188:191], v183 offset:3072
	ds_read_b128 v[192:195], v183 offset:4096
	ds_read_b128 v[196:199], v183 offset:5120
	ds_read_b128 v[200:203], v183 offset:6144
	ds_read_b128 v[204:207], v183 offset:7168
	global_load_lds_dwordx4 v[208:209], off
	v_lshl_add_u64 v[208:209], s[52:53], 0, v[174:175]
	s_add_i32 m0, s18, 0xe000
	s_nop 0
	global_load_lds_dwordx4 v[208:209], off
	s_waitcnt vmcnt(8)
	s_waitcnt lgkmcnt(0)
	s_barrier
	s_setprio 1
	s_waitcnt lgkmcnt(0)
	v_mfma_f32_16x16x32_bf16 v[158:161], v[60:63], v[162:165], v[158:161]
	v_mfma_f32_16x16x32_bf16 v[154:157], v[72:75], v[162:165], v[154:157]
	v_mfma_f32_16x16x32_bf16 v[142:145], v[60:63], v[184:187], v[142:145]
	v_mfma_f32_16x16x32_bf16 v[138:141], v[72:75], v[184:187], v[138:141]
	v_mfma_f32_16x16x32_bf16 v[126:129], v[60:63], v[192:195], v[126:129]
	v_mfma_f32_16x16x32_bf16 v[122:125], v[72:75], v[192:195], v[122:125]
	v_mfma_f32_16x16x32_bf16 v[110:113], v[60:63], v[200:203], v[110:113]
	v_mfma_f32_16x16x32_bf16 v[106:109], v[72:75], v[200:203], v[106:109]
	v_mfma_f32_16x16x32_bf16 v[158:161], v[64:67], v[176:179], v[158:161]
	v_mfma_f32_16x16x32_bf16 v[154:157], v[76:79], v[176:179], v[154:157]
	v_mfma_f32_16x16x32_bf16 v[142:145], v[64:67], v[188:191], v[142:145]
	v_mfma_f32_16x16x32_bf16 v[138:141], v[76:79], v[188:191], v[138:141]
	v_mfma_f32_16x16x32_bf16 v[126:129], v[64:67], v[196:199], v[126:129]
	v_mfma_f32_16x16x32_bf16 v[122:125], v[76:79], v[196:199], v[122:125]
	v_mfma_f32_16x16x32_bf16 v[110:113], v[64:67], v[204:207], v[110:113]
	v_mfma_f32_16x16x32_bf16 v[106:109], v[76:79], v[204:207], v[106:109]
	v_mfma_f32_16x16x32_bf16 v[150:153], v[82:85], v[162:165], v[150:153]
	v_mfma_f32_16x16x32_bf16 v[146:149], v[90:93], v[162:165], v[146:149]
	v_mfma_f32_16x16x32_bf16 v[134:137], v[82:85], v[184:187], v[134:137]
	v_mfma_f32_16x16x32_bf16 v[130:133], v[90:93], v[184:187], v[130:133]
	v_mfma_f32_16x16x32_bf16 v[118:121], v[82:85], v[192:195], v[118:121]
	v_mfma_f32_16x16x32_bf16 v[114:117], v[90:93], v[192:195], v[114:117]
	v_mfma_f32_16x16x32_bf16 v[102:105], v[82:85], v[200:203], v[102:105]
	v_mfma_f32_16x16x32_bf16 v[98:101], v[90:93], v[200:203], v[98:101]
	v_mfma_f32_16x16x32_bf16 v[150:153], v[86:89], v[176:179], v[150:153]
	v_mfma_f32_16x16x32_bf16 v[146:149], v[94:97], v[176:179], v[146:149]
	v_mfma_f32_16x16x32_bf16 v[134:137], v[86:89], v[188:191], v[134:137]
	v_mfma_f32_16x16x32_bf16 v[130:133], v[94:97], v[188:191], v[130:133]
	v_mfma_f32_16x16x32_bf16 v[118:121], v[86:89], v[196:199], v[118:121]
	v_mfma_f32_16x16x32_bf16 v[114:117], v[94:97], v[196:199], v[114:117]
	v_mfma_f32_16x16x32_bf16 v[102:105], v[86:89], v[204:207], v[102:105]
	v_mfma_f32_16x16x32_bf16 v[98:101], v[94:97], v[204:207], v[98:101]
	s_setprio 0
	s_barrier
	s_add_i32 s72, s72, s17
	v_lshl_add_u64 v[208:209], s[54:55], 0, v[80:81]
	s_mov_b32 m0, s72
	ds_read_b128 v[162:165], v183 offset:16384
	ds_read_b128 v[176:179], v183 offset:17408
	ds_read_b128 v[184:187], v183 offset:18432
	ds_read_b128 v[188:191], v183 offset:19456
	ds_read_b128 v[192:195], v183 offset:20480
	ds_read_b128 v[196:199], v183 offset:21504
	ds_read_b128 v[200:203], v183 offset:22528
	ds_read_b128 v[204:207], v183 offset:23552
	global_load_lds_dwordx4 v[208:209], off
	s_add_i32 m0, s72, 0x2000
	s_add_u32 s72, s54, 0x40000
	v_lshl_add_u64 v[210:211], s[54:55], 0, v[170:171]
	s_addc_u32 s73, s55, 0
	s_add_i32 s74, s74, s17
	global_load_lds_dwordx4 v[210:211], off
	v_lshl_add_u64 v[212:213], s[72:73], 0, v[80:81]
	s_mov_b32 m0, s74
	v_lshl_add_u64 v[214:215], s[56:57], 0, v[168:169]
	global_load_lds_dwordx4 v[212:213], off
	v_lshl_add_u64 v[212:213], s[72:73], 0, v[170:171]
	s_add_i32 m0, s74, 0x2000
	s_nop 0
	global_load_lds_dwordx4 v[212:213], off
	v_lshl_add_u64 v[212:213], s[56:57], 0, v[166:167]
	s_mov_b32 m0, s18
	s_nop 0
	global_load_lds_dwordx4 v[212:213], off
	s_mov_b32 m0, s19
	s_nop 0
	global_load_lds_dwordx4 v[214:215], off
	s_waitcnt vmcnt(8)
	s_waitcnt lgkmcnt(0)
	s_barrier
; #define PG8_STAGE(bufoff, gbase, voff) do { _Pragma("unroll") for (int _i = 0; _i < 2; ++_i) \
;         __builtin_amdgcn_global_load_lds((const unsigned*)((const char*)(gbase) + (voff)[_i]), (PG8_LAS unsigned*)(lds + (bufoff) + ldsw + _i * 8192), 16, 0, 0); } while (0)
; #define PG8_LDA(dst, b, h) do { _Pragma("unroll") for (int m = 0; m < 4; ++m) _Pragma("unroll") for (int k = 0; k < 2; ++k) dst[m][k] = *(const PG8_LAS bf16x8*)(lds + PG8_SA(b, h) + aoff + m * 2048 + k * 1024); } while (0)
; #define PG8_LDB(dst, b, h) do { _Pragma("unroll") for (int n = 0; n < 2; ++n) _Pragma("unroll") for (int k = 0; k < 2; ++k) dst[n][k] = *(const PG8_LAS bf16x8*)(lds + PG8_SB(b, h) + boff + n * 2048 + k * 1024); } while (0)
; #define PG8_MMA(ai, bj, At, Bt) do { __builtin_amdgcn_s_setprio(1); _Pragma("unroll") for (int m = 0; m < 4; ++m) _Pragma("unroll") for (int n = 0; n < 2; ++n) _Pragma("unroll") for (int k = 0; k < 2; ++k) \
;         acc[ai][bj][m][n] = __builtin_amdgcn_mfma_f32_16x16x32_bf16(Bt[n][k], At[m][k], acc[ai][bj][m][n], 0, 0, 0); __builtin_amdgcn_s_setprio(0); } while (0)
; #define PG8_WAIT_V(n) asm volatile("s_waitcnt vmcnt(" #n ")" ::: "memory")
; #define PG8_WAIT_L(n) asm volatile("s_waitcnt lgkmcnt(" #n ")" ::: "memory")
; #define PG8_BAR __builtin_amdgcn_s_barrier()
; #define PG8_SCHED __builtin_amdgcn_sched_barrier(0)
; template <class Epi, class Sched, bool ALIGN_EPI = false, bool SP2 = false>
; __device__ __forceinline__ void gemm_phase(PG8_LAS unsigned char* lds, const Gemm g, const Sched& S, const Epi& E, int tid_in) {
;     ...
;             PG8_WAIT_V(8); PG8_WAIT_L(0); PG8_BAR; PG8_MMA(1, 0, At, B0); PG8_MMA(1, 1, At, B1); PG8_BAR; PG8_SCHED;
;             PG8_LDB(B0, 1, 0); PG8_LDB(B1, 1, 1); PG8_SCHED; PG8_LDA(At, 1, 0); PG8_STAGE(PG8_SA(0, 1), a2 + hstep, voffA);
;             PG8_WAIT_V(8); PG8_WAIT_L(0); PG8_BAR; PG8_MMA(0, 0, At, B0); PG8_MMA(0, 1, At, B1); PG8_BAR; PG8_SCHED;
	s_setprio 1
	s_waitcnt lgkmcnt(0)
	v_mfma_f32_16x16x32_bf16 v[68:71], v[60:63], v[162:165], v[68:71]
	v_mfma_f32_16x16x32_bf16 v[56:59], v[72:75], v[162:165], v[56:59]
	v_mfma_f32_16x16x32_bf16 v[44:47], v[60:63], v[184:187], v[44:47]
	v_mfma_f32_16x16x32_bf16 v[40:43], v[72:75], v[184:187], v[40:43]
	v_mfma_f32_16x16x32_bf16 v[28:31], v[60:63], v[192:195], v[28:31]
	v_mfma_f32_16x16x32_bf16 v[24:27], v[72:75], v[192:195], v[24:27]
	v_mfma_f32_16x16x32_bf16 v[12:15], v[60:63], v[200:203], v[12:15]
	v_mfma_f32_16x16x32_bf16 v[8:11], v[72:75], v[200:203], v[8:11]
	v_mfma_f32_16x16x32_bf16 v[68:71], v[64:67], v[176:179], v[68:71]
	v_mfma_f32_16x16x32_bf16 v[56:59], v[76:79], v[176:179], v[56:59]
	v_mfma_f32_16x16x32_bf16 v[44:47], v[64:67], v[188:191], v[44:47]
	v_mfma_f32_16x16x32_bf16 v[40:43], v[76:79], v[188:191], v[40:43]
	v_mfma_f32_16x16x32_bf16 v[28:31], v[64:67], v[196:199], v[28:31]
	v_mfma_f32_16x16x32_bf16 v[24:27], v[76:79], v[196:199], v[24:27]
	v_mfma_f32_16x16x32_bf16 v[12:15], v[64:67], v[204:207], v[12:15]
	v_mfma_f32_16x16x32_bf16 v[8:11], v[76:79], v[204:207], v[8:11]
	v_mfma_f32_16x16x32_bf16 v[52:55], v[82:85], v[162:165], v[52:55]
	v_mfma_f32_16x16x32_bf16 v[48:51], v[90:93], v[162:165], v[48:51]
	v_mfma_f32_16x16x32_bf16 v[36:39], v[82:85], v[184:187], v[36:39]
	v_mfma_f32_16x16x32_bf16 v[32:35], v[90:93], v[184:187], v[32:35]
	v_mfma_f32_16x16x32_bf16 v[20:23], v[82:85], v[192:195], v[20:23]
	v_mfma_f32_16x16x32_bf16 v[16:19], v[90:93], v[192:195], v[16:19]
	v_mfma_f32_16x16x32_bf16 v[4:7], v[82:85], v[200:203], v[4:7]
	v_mfma_f32_16x16x32_bf16 v[0:3], v[90:93], v[200:203], v[0:3]
	v_mfma_f32_16x16x32_bf16 v[52:55], v[86:89], v[176:179], v[52:55]
	v_mfma_f32_16x16x32_bf16 v[48:51], v[94:97], v[176:179], v[48:51]
	v_mfma_f32_16x16x32_bf16 v[36:39], v[86:89], v[188:191], v[36:39]
	v_mfma_f32_16x16x32_bf16 v[32:35], v[94:97], v[188:191], v[32:35]
	v_mfma_f32_16x16x32_bf16 v[20:23], v[86:89], v[196:199], v[20:23]
	v_mfma_f32_16x16x32_bf16 v[16:19], v[94:97], v[196:199], v[16:19]
	v_mfma_f32_16x16x32_bf16 v[4:7], v[86:89], v[204:207], v[4:7]
	v_mfma_f32_16x16x32_bf16 v[0:3], v[94:97], v[204:207], v[0:3]
	s_setprio 0
	s_barrier
	s_add_i32 s72, 0, 0x18000
	s_add_i32 s73, 0, 0x1c000
	v_add_u32_e32 v76, s72, v182
	v_add_u32_e32 v94, s73, v182
	ds_read_b128 v[60:63], v76
	ds_read_b128 v[64:67], v76 offset:1024
	ds_read_b128 v[72:75], v76 offset:2048
	ds_read_b128 v[76:79], v76 offset:3072
	ds_read_b128 v[82:85], v94
	ds_read_b128 v[86:89], v94 offset:1024
	ds_read_b128 v[90:93], v94 offset:2048
	ds_read_b128 v[94:97], v94 offset:3072
	s_add_u32 s56, s56, 0x40000
	s_addc_u32 s57, s57, 0
	s_mov_b32 m0, s58
	v_lshl_add_u64 v[226:227], s[56:57], 0, v[166:167]
	ds_read_b128 v[162:165], v183 offset:32768
	ds_read_b128 v[176:179], v183 offset:33792
	ds_read_b128 v[184:187], v183 offset:34816
	ds_read_b128 v[188:191], v183 offset:35840
	ds_read_b128 v[192:195], v183 offset:36864
	ds_read_b128 v[196:199], v183 offset:37888
	ds_read_b128 v[200:203], v183 offset:38912
	ds_read_b128 v[204:207], v183 offset:39936
	global_load_lds_dwordx4 v[226:227], off
	v_lshl_add_u64 v[226:227], s[56:57], 0, v[168:169]
	s_mov_b32 m0, s59
	s_nop 0
	global_load_lds_dwordx4 v[226:227], off
	s_waitcnt vmcnt(8)
	s_waitcnt lgkmcnt(0)
	s_barrier
	s_setprio 1
	s_waitcnt lgkmcnt(0)
	v_mfma_f32_16x16x32_bf16 v[158:161], v[60:63], v[162:165], v[158:161]
	v_mfma_f32_16x16x32_bf16 v[154:157], v[72:75], v[162:165], v[154:157]
	v_mfma_f32_16x16x32_bf16 v[142:145], v[60:63], v[184:187], v[142:145]
	v_mfma_f32_16x16x32_bf16 v[138:141], v[72:75], v[184:187], v[138:141]
	v_mfma_f32_16x16x32_bf16 v[126:129], v[60:63], v[192:195], v[126:129]
	v_mfma_f32_16x16x32_bf16 v[122:125], v[72:75], v[192:195], v[122:125]
	v_mfma_f32_16x16x32_bf16 v[110:113], v[60:63], v[200:203], v[110:113]
	v_mfma_f32_16x16x32_bf16 v[106:109], v[72:75], v[200:203], v[106:109]
	v_mfma_f32_16x16x32_bf16 v[158:161], v[64:67], v[176:179], v[158:161]
	v_mfma_f32_16x16x32_bf16 v[154:157], v[76:79], v[176:179], v[154:157]
	v_mfma_f32_16x16x32_bf16 v[142:145], v[64:67], v[188:191], v[142:145]
	v_mfma_f32_16x16x32_bf16 v[138:141], v[76:79], v[188:191], v[138:141]
	v_mfma_f32_16x16x32_bf16 v[126:129], v[64:67], v[196:199], v[126:129]
	v_mfma_f32_16x16x32_bf16 v[122:125], v[76:79], v[196:199], v[122:125]
	v_mfma_f32_16x16x32_bf16 v[110:113], v[64:67], v[204:207], v[110:113]
	v_mfma_f32_16x16x32_bf16 v[106:109], v[76:79], v[204:207], v[106:109]
	v_mfma_f32_16x16x32_bf16 v[150:153], v[82:85], v[162:165], v[150:153]
	v_mfma_f32_16x16x32_bf16 v[146:149], v[90:93], v[162:165], v[146:149]
	v_mfma_f32_16x16x32_bf16 v[134:137], v[82:85], v[184:187], v[134:137]
	v_mfma_f32_16x16x32_bf16 v[130:133], v[90:93], v[184:187], v[130:133]
	v_mfma_f32_16x16x32_bf16 v[118:121], v[82:85], v[192:195], v[118:121]
	v_mfma_f32_16x16x32_bf16 v[114:117], v[90:93], v[192:195], v[114:117]
	v_mfma_f32_16x16x32_bf16 v[102:105], v[82:85], v[200:203], v[102:105]
	v_mfma_f32_16x16x32_bf16 v[98:101], v[90:93], v[200:203], v[98:101]
	v_mfma_f32_16x16x32_bf16 v[150:153], v[86:89], v[176:179], v[150:153]
	v_mfma_f32_16x16x32_bf16 v[146:149], v[94:97], v[176:179], v[146:149]
	v_mfma_f32_16x16x32_bf16 v[134:137], v[86:89], v[188:191], v[134:137]
	v_mfma_f32_16x16x32_bf16 v[130:133], v[94:97], v[188:191], v[130:133]
	v_mfma_f32_16x16x32_bf16 v[118:121], v[86:89], v[196:199], v[118:121]
	v_mfma_f32_16x16x32_bf16 v[114:117], v[94:97], v[196:199], v[114:117]
	v_mfma_f32_16x16x32_bf16 v[102:105], v[86:89], v[204:207], v[102:105]
	v_mfma_f32_16x16x32_bf16 v[98:101], v[94:97], v[204:207], v[98:101]
	s_setprio 0
	s_barrier
; #define PG8_STAGE(bufoff, gbase, voff) do { _Pragma("unroll") for (int _i = 0; _i < 2; ++_i) \
;         __builtin_amdgcn_global_load_lds((const unsigned*)((const char*)(gbase) + (voff)[_i]), (PG8_LAS unsigned*)(lds + (bufoff) + ldsw + _i * 8192), 16, 0, 0); } while (0)
; #define PG8_LDA(dst, b, h) do { _Pragma("unroll") for (int m = 0; m < 4; ++m) _Pragma("unroll") for (int k = 0; k < 2; ++k) dst[m][k] = *(const PG8_LAS bf16x8*)(lds + PG8_SA(b, h) + aoff + m * 2048 + k * 1024); } while (0)
; #define PG8_MMA(ai, bj, At, Bt) do { __builtin_amdgcn_s_setprio(1); _Pragma("unroll") for (int m = 0; m < 4; ++m) _Pragma("unroll") for (int n = 0; n < 2; ++n) _Pragma("unroll") for (int k = 0; k < 2; ++k) \
;         acc[ai][bj][m][n] = __builtin_amdgcn_mfma_f32_16x16x32_bf16(Bt[n][k], At[m][k], acc[ai][bj][m][n], 0, 0, 0); __builtin_amdgcn_s_setprio(0); } while (0)
; #define PG8_WAIT_V(n) asm volatile("s_waitcnt vmcnt(" #n ")" ::: "memory")
; #define PG8_WAIT_L(n) asm volatile("s_waitcnt lgkmcnt(" #n ")" ::: "memory")
; #define PG8_BAR __builtin_amdgcn_s_barrier()
; #define PG8_SCHED __builtin_amdgcn_sched_barrier(0)
; template <class Epi, class Sched, bool ALIGN_EPI = false, bool SP2 = false>
; __device__ __forceinline__ void gemm_phase(PG8_LAS unsigned char* lds, const Gemm g, const Sched& S, const Epi& E, int tid_in) {
;     ...
;             PG8_LDA(At, 1, 1); PG8_STAGE(PG8_SB(1, 0), b3, voffB); PG8_STAGE(PG8_SB(1, 1), b3 + hstep, voffB); PG8_STAGE(PG8_SA(1, 0), a3, voffA);
;             PG8_WAIT_V(8); PG8_WAIT_L(0); PG8_BAR; PG8_MMA(1, 0, At, B0); PG8_MMA(1, 1, At, B1); PG8_BAR; PG8_SCHED;
;     __device__ __forceinline__ void operator()(const pg8::f32x4 (&acc)[2][2][4][2], const pg8::Unit& u, int wr, int wc, int fr, int fq) const {
;     ...
; #pragma unroll
;         for (int bj = 0; bj < 2; ++bj) { const float* cp = c12 + (size_t)(u.pn * 256 + bj * 128 + cl) * 2; craw[bj][0] = *(const f32x4*)cp; craw[bj][1] = *(const f32x4*)(cp + 4); craw[bj][2] = *(const f32x4*)(cp + 8); craw[bj][3] = *(const f32x4*)(cp + 12); }
;         ln_table(st, u.pm, key, wr, wc, fr, fq);
	s_add_i32 s56, s72, s17
	v_lshl_add_u64 v[208:209], v[208:209], 0, s[6:7]
	s_mov_b32 m0, s56
	ds_read_b128 v[162:165], v183 offset:49152
	ds_read_b128 v[176:179], v183 offset:50176
	ds_read_b128 v[184:187], v183 offset:51200
	ds_read_b128 v[188:191], v183 offset:52224
	ds_read_b128 v[192:195], v183 offset:53248
	ds_read_b128 v[196:199], v183 offset:54272
	ds_read_b128 v[200:203], v183 offset:55296
	ds_read_b128 v[204:207], v183 offset:56320
	global_load_lds_dwordx4 v[208:209], off
	s_add_i32 m0, s56, 0x2000
	s_add_u32 s54, s54, 0x40080
	v_lshl_add_u64 v[208:209], v[210:211], 0, s[6:7]
	s_addc_u32 s55, s55, 0
	s_add_i32 s56, s73, s17
	global_load_lds_dwordx4 v[208:209], off
	v_lshl_add_u64 v[208:209], s[54:55], 0, v[80:81]
	s_mov_b32 m0, s56
	s_nop 0
	global_load_lds_dwordx4 v[208:209], off
	v_lshl_add_u64 v[208:209], s[54:55], 0, v[170:171]
	s_add_i32 m0, s56, 0x2000
	s_nop 0
	global_load_lds_dwordx4 v[208:209], off
	v_lshl_add_u64 v[208:209], v[212:213], 0, s[6:7]
	s_mov_b32 m0, s62
	s_nop 0
	global_load_lds_dwordx4 v[208:209], off
	v_lshl_add_u64 v[208:209], v[214:215], 0, s[6:7]
	s_mov_b32 m0, s63
	s_nop 0
	global_load_lds_dwordx4 v[208:209], off
	s_waitcnt vmcnt(8)
	s_waitcnt lgkmcnt(0)
	s_barrier
	s_setprio 1
	s_waitcnt lgkmcnt(0)
	v_mfma_f32_16x16x32_bf16 v[68:71], v[60:63], v[162:165], v[68:71]
	v_mfma_f32_16x16x32_bf16 v[56:59], v[72:75], v[162:165], v[56:59]
	v_mfma_f32_16x16x32_bf16 v[44:47], v[60:63], v[184:187], v[44:47]
	v_mfma_f32_16x16x32_bf16 v[40:43], v[72:75], v[184:187], v[40:43]
	v_mfma_f32_16x16x32_bf16 v[28:31], v[60:63], v[192:195], v[28:31]
	v_mfma_f32_16x16x32_bf16 v[24:27], v[72:75], v[192:195], v[24:27]
	v_mfma_f32_16x16x32_bf16 v[12:15], v[60:63], v[200:203], v[12:15]
	v_mfma_f32_16x16x32_bf16 v[8:11], v[72:75], v[200:203], v[8:11]
	v_mfma_f32_16x16x32_bf16 v[68:71], v[64:67], v[176:179], v[68:71]
	v_mfma_f32_16x16x32_bf16 v[56:59], v[76:79], v[176:179], v[56:59]
	v_mfma_f32_16x16x32_bf16 v[44:47], v[64:67], v[188:191], v[44:47]
	v_mfma_f32_16x16x32_bf16 v[40:43], v[76:79], v[188:191], v[40:43]
	v_mfma_f32_16x16x32_bf16 v[28:31], v[64:67], v[196:199], v[28:31]
	v_mfma_f32_16x16x32_bf16 v[24:27], v[76:79], v[196:199], v[24:27]
	v_mfma_f32_16x16x32_bf16 v[12:15], v[64:67], v[204:207], v[12:15]
	v_mfma_f32_16x16x32_bf16 v[8:11], v[76:79], v[204:207], v[8:11]
	v_mfma_f32_16x16x32_bf16 v[52:55], v[82:85], v[162:165], v[52:55]
	v_mfma_f32_16x16x32_bf16 v[48:51], v[90:93], v[162:165], v[48:51]
	v_mfma_f32_16x16x32_bf16 v[36:39], v[82:85], v[184:187], v[36:39]
	v_mfma_f32_16x16x32_bf16 v[32:35], v[90:93], v[184:187], v[32:35]
	v_mfma_f32_16x16x32_bf16 v[20:23], v[82:85], v[192:195], v[20:23]
	v_mfma_f32_16x16x32_bf16 v[16:19], v[90:93], v[192:195], v[16:19]
	v_mfma_f32_16x16x32_bf16 v[4:7], v[82:85], v[200:203], v[4:7]
	v_mfma_f32_16x16x32_bf16 v[0:3], v[90:93], v[200:203], v[0:3]
	v_mfma_f32_16x16x32_bf16 v[52:55], v[86:89], v[176:179], v[52:55]
	v_mfma_f32_16x16x32_bf16 v[48:51], v[94:97], v[176:179], v[48:51]
	v_mfma_f32_16x16x32_bf16 v[36:39], v[86:89], v[188:191], v[36:39]
	v_mfma_f32_16x16x32_bf16 v[32:35], v[94:97], v[188:191], v[32:35]
	v_mfma_f32_16x16x32_bf16 v[20:23], v[86:89], v[196:199], v[20:23]
	v_mfma_f32_16x16x32_bf16 v[16:19], v[94:97], v[196:199], v[16:19]
	v_mfma_f32_16x16x32_bf16 v[4:7], v[86:89], v[204:207], v[4:7]
	v_mfma_f32_16x16x32_bf16 v[0:3], v[94:97], v[204:207], v[0:3]
	s_setprio 0
	s_barrier
	s_add_i32 s71, s71, 2
	s_add_u32 s52, s52, 0x100
	s_addc_u32 s53, s53, 0
	s_add_u32 s69, s69, 0x100
	s_addc_u32 s70, s70, 0
	s_cmp_gt_u32 s71, 13
	s_cbranch_scc0 .LBB0_1601
	v_mov_b32_e32 v163, v181
	v_mov_b32_e32 v162, v180
	s_add_i32 s43, s66, s8
	v_lshl_add_u32 v178, v163, 3, s61
	v_lshl_add_u32 v60, s9, 8, v178
	v_ashrrev_i32_e32 v61, 31, v60
	v_lshl_add_u64 v[62:63], v[60:61], 3, s[4:5]
	v_add_u32_e32 v60, 0x80, v60
	v_ashrrev_i32_e32 v61, 31, v60
	v_lshl_add_u64 v[90:91], v[60:61], 3, s[4:5]
	global_load_dwordx4 v[64:67], v[62:63], off offset:48
	global_load_dwordx4 v[86:89], v[62:63], off offset:32
	global_load_dwordx4 v[76:79], v[62:63], off offset:16
	global_load_dwordx4 v[94:97], v[62:63], off
	s_nop 0
	global_load_dwordx4 v[60:63], v[90:91], off offset:48
	global_load_dwordx4 v[82:85], v[90:91], off offset:32
	global_load_dwordx4 v[72:75], v[90:91], off offset:16
	s_nop 0
	global_load_dwordx4 v[90:93], v[90:91], off
	s_and_b64 vcc, exec, s[40:41]
	s_cbranch_vccz .LBB0_1604
	s_barrier
.LBB0_1604:
	ds_read_b32 v164, v223
	s_waitcnt lgkmcnt(0)
	v_readfirstlane_b32 s0, v164
	s_cmp_eq_u32 s0, s43
	s_cbranch_scc1 .LBB0_1610
	v_lshlrev_b32_e32 v163, 4, v163
	v_add3_u32 v163, s64, v162, v163
	s_movk_i32 s0, 0x100
	v_cmp_gt_i32_e32 vcc, s0, v163
	s_and_saveexec_b64 s[0:1], vcc
	s_cbranch_execz .LBB0_1607
	v_lshl_add_u32 v164, s8, 8, v163
	v_ashrrev_i32_e32 v165, 31, v164
	v_lshlrev_b64 v[164:165], 7, v[164:165]
	v_lshl_add_u64 v[164:165], s[44:45], 0, v[164:165]
	global_load_dwordx4 v[184:187], v[164:165], off
	global_load_dwordx4 v[188:191], v[164:165], off offset:16
	global_load_dwordx4 v[192:195], v[164:165], off offset:32
	global_load_dwordx4 v[196:199], v[164:165], off offset:48
	global_load_dwordx4 v[200:203], v[164:165], off offset:64
	global_load_dwordx4 v[204:207], v[164:165], off offset:80
	global_load_dwordx4 v[208:211], v[164:165], off offset:96
	global_load_dwordx4 v[212:215], v[164:165], off offset:112
	s_mov_b32 s24, 0x3a800000
	s_waitcnt vmcnt(0)
	v_pk_add_f32 v[164:165], v[184:185], v[186:187]
	v_pk_add_f32 v[176:177], v[188:189], v[190:191]
	v_pk_add_f32 v[164:165], v[164:165], 0 op_sel_hi:[1,0]
	v_pk_add_f32 v[184:185], v[192:193], v[194:195]
	v_pk_add_f32 v[164:165], v[164:165], v[176:177]
	v_pk_add_f32 v[186:187], v[196:197], v[198:199]
	v_pk_add_f32 v[164:165], v[164:165], v[184:185]
	v_pk_add_f32 v[188:189], v[200:201], v[202:203]
	v_pk_add_f32 v[164:165], v[164:165], v[186:187]
	v_pk_add_f32 v[190:191], v[204:205], v[206:207]
	v_pk_add_f32 v[164:165], v[164:165], v[188:189]
	v_pk_add_f32 v[192:193], v[208:209], v[210:211]
	v_pk_add_f32 v[164:165], v[164:165], v[190:191]
	v_pk_add_f32 v[176:177], v[212:213], v[214:215]
	v_pk_add_f32 v[164:165], v[164:165], v[192:193]
	s_nop 0
	v_pk_add_f32 v[164:165], v[164:165], v[176:177]
	v_lshl_add_u32 v176, v163, 3, v225
	v_pk_mul_f32 v[164:165], v[164:165], s[24:25] op_sel_hi:[1,0]
	s_nop 0
	v_fma_f32 v165, -v164, v164, v165
	v_max_f32_e32 v165, 0, v165
	v_add_f32_e32 v165, 0x3727c5ac, v165
	v_rsq_f32_e32 v165, v165
	ds_write_b64 v176, v[164:165]
